# GLA pass-0 units also visited most-recently-written row groups first (on top of the attention reorder)
# baseline (speedup 1.0000x reference)
.LBB0_572:
	s_lshr_b32 s93, s33, 6
	s_mul_i32 s93, s93, 0xc0
	s_and_b32 s94, s33, 63
	s_add_i32 s93, s93, s94
	s_add_i32 s33, s93, 0x80
	s_mov_b32 s93, 0
	v_ashrrev_i32_e32 v1, 2, v187
	s_and_b32 s6, s33, 1
	v_and_b32_e32 v1, 0xffffffc0, v1
	v_lshrrev_b32_e32 v2, 1, v187
	v_and_b32_e32 v0, 31, v187
	v_lshl_add_u32 v1, s6, 7, v1
	v_and_b32_e32 v2, 32, v2
	v_or3_b32 v10, v2, v0, v1
	v_and_b32_e32 v0, 0x80, v187
	s_add_u32 s8, s41, 0x3790000
	v_mov_b32_e32 v2, 0x4500
	v_mov_b32_e32 v3, 0x100
	v_cmp_eq_u32_e32 vcc, 0, v0
	s_addc_u32 s9, s42, 0
	v_mov_b32_e32 v109, 0
	v_cndmask_b32_e32 v108, v2, v3, vcc
	v_lshl_add_u64 v[2:3], s[8:9], 0, v[108:109]
	v_ashrrev_i32_e32 v11, 31, v10
	v_lshlrev_b32_e32 v0, 8, v187
	v_lshl_add_u64 v[2:3], v[10:11], 2, v[2:3]
	v_and_b32_e32 v108, 0x2000, v0
	v_lshl_add_u64 v[12:13], v[2:3], 0, v[108:109]
	s_movk_i32 s18, 0x1000
	v_add_co_u32_e64 v14, s[4:5], s18, v12
	v_mov_b32_e32 v0, 0x2140
	s_nop 0
	v_addc_co_u32_e64 v15, s[4:5], 0, v13, s[4:5]
	global_load_dword v2, v[12:13], off
	global_load_dword v3, v[12:13], off offset:1024
	global_load_dword v4, v[12:13], off offset:2048
	global_load_dword v5, v[12:13], off offset:3072
	global_load_dword v6, v[14:15], off
	global_load_dword v7, v[14:15], off offset:1024
	global_load_dword v8, v[14:15], off offset:2048
	global_load_dword v9, v[14:15], off offset:3072
	v_mov_b32_e32 v11, 0x1040
	v_cndmask_b32_e32 v0, v0, v11, vcc
	v_add_u32_e32 v10, v10, v0
	v_ashrrev_i32_e32 v11, 31, v10
	v_lshl_add_u64 v[10:11], v[10:11], 2, s[8:9]
	global_load_dword v0, v[10:11], off
	s_load_dwordx2 s[4:5], s[0:1], 0xa0
	s_cmpk_lt_i32 s33, 0x600
	s_waitcnt lgkmcnt(0)
	v_mov_b32_e32 v10, s5
	v_mov_b32_e32 v11, s4
	s_nop 0
	v_readfirstlane_b32 s8, v11
	v_readfirstlane_b32 s9, v10
	s_cbranch_scc0 .LBB0_591
	s_lshl_b32 s4, s33, 5
	v_lshrrev_b32_e32 v11, 2, v187
	s_and_b32 s7, s4, 0xffffffc0
	v_and_or_b32 v12, v11, 48, s7
	s_add_u32 s10, s41, 0xf800000
	v_ashrrev_i32_e32 v13, 31, v12
	s_addc_u32 s11, s42, 0
	v_and_or_b32 v10, v187, 63, v1
	v_lshlrev_b64 v[12:13], 9, v[12:13]
	v_lshl_add_u64 v[12:13], s[10:11], 0, v[12:13]
	v_ashrrev_i32_e32 v11, 31, v10
	v_lshl_add_u64 v[10:11], v[10:11], 1, v[12:13]
	global_load_ushort v1, v[10:11], off
	global_load_ushort v16, v[10:11], off offset:512
	global_load_ushort v17, v[10:11], off offset:1024
	global_load_ushort v18, v[10:11], off offset:1536
	global_load_ushort v19, v[10:11], off offset:2048
	global_load_ushort v20, v[10:11], off offset:2560
	global_load_ushort v21, v[10:11], off offset:3072
	global_load_ushort v22, v[10:11], off offset:3584
	v_add_co_u32_e32 v10, vcc, s18, v10
	s_add_u32 s19, s41, 0x11000000
	s_nop 0
	v_addc_co_u32_e32 v11, vcc, 0, v11, vcc
	global_load_ushort v23, v[10:11], off
	global_load_ushort v24, v[10:11], off offset:512
	global_load_ushort v25, v[10:11], off offset:1024
	global_load_ushort v26, v[10:11], off offset:1536
	global_load_ushort v27, v[10:11], off offset:2048
	global_load_ushort v28, v[10:11], off offset:2560
	global_load_ushort v29, v[10:11], off offset:3072
	global_load_ushort v30, v[10:11], off offset:3584
	v_ashrrev_i32_e32 v10, 3, v187
	s_addc_u32 s20, s42, 0
	v_add_u32_e32 v10, s7, v10
	s_add_u32 s12, s41, 0x17000000
	v_ashrrev_i32_e32 v11, 31, v10
	s_addc_u32 s13, s42, 0
	v_lshlrev_b64 v[10:11], 7, v[10:11]
	v_lshlrev_b32_e32 v12, 4, v187
	s_lshl_b32 s4, s6, 9
	v_ashrrev_i32_e32 v14, 5, v187
	v_lshl_add_u64 v[10:11], s[12:13], 0, v[10:11]
	v_and_b32_e32 v108, 0x70, v12
	s_add_u32 s4, s19, s4
	v_add_u32_e32 v14, s7, v14
	v_lshl_add_u64 v[10:11], v[10:11], 0, v[108:109]
	s_addc_u32 s5, s20, 0
	v_and_b32_e32 v108, 0x1f0, v12
	v_ashrrev_i32_e32 v15, 31, v14
	v_lshl_add_u64 v[12:13], s[4:5], 0, v[108:109]
	v_lshlrev_b64 v[14:15], 10, v[14:15]
	v_lshl_add_u64 v[14:15], v[12:13], 0, v[14:15]
	global_load_dwordx4 v[88:91], v[10:11], off
	global_load_dwordx4 v[92:95], v[14:15], off
	v_add_u32_e32 v10, 0x200, v187
	v_ashrrev_i32_e32 v10, 5, v10
	v_add_u32_e32 v14, 0x400, v187
	v_add_u32_e32 v10, s7, v10
	v_ashrrev_i32_e32 v14, 5, v14
	v_ashrrev_i32_e32 v11, 31, v10
	v_add_u32_e32 v14, s7, v14
	v_lshlrev_b64 v[10:11], 10, v[10:11]
	v_ashrrev_i32_e32 v15, 31, v14
	v_lshl_add_u64 v[10:11], v[12:13], 0, v[10:11]
	v_lshlrev_b64 v[14:15], 10, v[14:15]
	v_lshl_add_u64 v[14:15], v[12:13], 0, v[14:15]
	global_load_dwordx4 v[96:99], v[10:11], off
	global_load_dwordx4 v[100:103], v[14:15], off
	v_add_u32_e32 v10, 0x600, v187
	v_ashrrev_i32_e32 v10, 5, v10
	v_add_u32_e32 v10, s7, v10
	v_ashrrev_i32_e32 v11, 31, v10
	v_lshlrev_b64 v[10:11], 10, v[10:11]
	v_lshl_add_u64 v[10:11], v[12:13], 0, v[10:11]
	global_load_dwordx4 v[104:107], v[10:11], off
	s_waitcnt vmcnt(28)
	v_cvt_pk_bf16_f32 v10, v3, 0
	v_lshlrev_b32_e32 v11, 16, v10
	s_waitcnt vmcnt(26)
	v_cvt_pk_bf16_f32 v12, v5, 0
	v_lshlrev_b32_e32 v13, 16, v12
	s_waitcnt vmcnt(24)
	v_cvt_pk_bf16_f32 v14, v7, 0
	v_lshlrev_b32_e32 v15, 16, v14
	s_add_u32 s14, s41, 0x3600000
	v_cvt_pk_bf16_f32 v80, v2, v3
	v_cvt_pk_bf16_f32 v81, v4, v5
	v_cvt_pk_bf16_f32 v82, v6, v7
	s_waitcnt vmcnt(22)
	v_cvt_pk_bf16_f32 v83, v8, v9
	s_addc_u32 s15, s42, 0
	s_lshl_b32 s21, s33, 1
	s_lshl_b32 s26, s40, 1
	s_movk_i32 s27, 0x220
	s_movk_i32 s28, 0x90
	s_waitcnt vmcnt(20)
	v_and_b32_e32 v110, 0xffff, v1
	v_cvt_pk_bf16_f32 v1, v2, 0
	v_lshlrev_b32_e32 v10, 16, v1
	v_cvt_pk_bf16_f32 v1, v4, 0
	v_lshlrev_b32_e32 v12, 16, v1
	v_cvt_pk_bf16_f32 v1, v6, 0
	s_waitcnt vmcnt(19)
	v_and_b32_e32 v111, 0xffff, v16
	v_lshlrev_b32_e32 v14, 16, v1
	v_cvt_pk_bf16_f32 v1, v8, 0
	v_cvt_pk_bf16_f32 v16, v9, 0
	s_waitcnt vmcnt(18)
	v_and_b32_e32 v112, 0xffff, v17
	v_lshlrev_b32_e32 v17, 16, v16
	v_lshlrev_b32_e32 v16, 16, v1
	v_pk_add_f32 v[10:11], v[2:3], v[10:11] neg_lo:[0,1] neg_hi:[0,1]
	v_pk_add_f32 v[12:13], v[4:5], v[12:13] neg_lo:[0,1] neg_hi:[0,1]
	v_pk_add_f32 v[14:15], v[6:7], v[14:15] neg_lo:[0,1] neg_hi:[0,1]
	v_pk_add_f32 v[16:17], v[8:9], v[16:17] neg_lo:[0,1] neg_hi:[0,1]
	s_waitcnt vmcnt(17)
	v_and_b32_e32 v113, 0xffff, v18
	s_waitcnt vmcnt(16)
	v_and_b32_e32 v114, 0xffff, v19
	s_waitcnt vmcnt(15)
	v_and_b32_e32 v115, 0xffff, v20
	s_waitcnt vmcnt(14)
	v_and_b32_e32 v116, 0xffff, v21
	s_waitcnt vmcnt(13)
	v_and_b32_e32 v117, 0xffff, v22
	s_waitcnt vmcnt(12)
	v_and_b32_e32 v118, 0xffff, v23
	s_waitcnt vmcnt(11)
	v_and_b32_e32 v119, 0xffff, v24
	s_waitcnt vmcnt(10)
	v_and_b32_e32 v120, 0xffff, v25
	s_waitcnt vmcnt(9)
	v_and_b32_e32 v121, 0xffff, v26
	s_waitcnt vmcnt(8)
	v_and_b32_e32 v122, 0xffff, v27
	s_waitcnt vmcnt(7)
	v_and_b32_e32 v123, 0xffff, v28
	s_waitcnt vmcnt(6)
	v_and_b32_e32 v124, 0xffff, v29
	s_waitcnt vmcnt(5)
	v_and_b32_e32 v125, 0xffff, v30
	v_cvt_pk_bf16_f32 v84, v10, v11
	v_cvt_pk_bf16_f32 v85, v12, v13
	v_cvt_pk_bf16_f32 v86, v14, v15
	v_cvt_pk_bf16_f32 v87, v16, v17
	v_mov_b32_e32 v1, v0
	v_mov_b32_e32 v2, v0
	v_mov_b32_e32 v3, v0
	v_mov_b32_e32 v4, v0
	v_mov_b32_e32 v5, v0
	v_mov_b32_e32 v6, v0
	v_mov_b32_e32 v7, v0
	v_mov_b32_e32 v8, v0
	v_mov_b32_e32 v9, v0
	v_mov_b32_e32 v10, v0
	v_mov_b32_e32 v11, v0
	v_mov_b32_e32 v12, v0
	v_mov_b32_e32 v13, v0
	v_mov_b32_e32 v14, v0
	v_mov_b32_e32 v15, v0
	s_branch .LBB0_575
.LBB0_574:
	v_and_b32_e32 v16, 16, v54
	v_and_b32_e32 v18, 0xfffff00, v54
	v_lshlrev_b32_e32 v19, 5, v126
	v_or3_b32 v18, v19, v18, v55
	v_lshl_or_b32 v16, v127, 6, v16
	v_and_b32_e32 v17, 12, v17
	v_or3_b32 v16, v17, v16, v58
	v_mul_lo_u32 v17, v18, s28
	v_add_u32_e32 v47, 0, v17
	v_lshl_add_u32 v20, v56, 4, v47
	v_lshlrev_b32_e32 v68, 1, v16
	ds_read_b128 v[16:19], v20 offset:47104
	v_bfe_u32 v37, v54, 2, 2
	v_lshlrev_b32_e32 v46, 3, v56
	v_or_b32_e32 v21, v46, v37
	v_mul_u32_u24_e32 v21, 0x220, v21
	v_add3_u32 v21, 0, v21, v68
	ds_read_b64_tr_b16 v[32:33], v21 offset:12288
	ds_read_b64_tr_b16 v[34:35], v21 offset:14464
	ds_read_b64_tr_b16 v[40:41], v21 offset:14528
	ds_read_b64_tr_b16 v[38:39], v21 offset:12352
	ds_read_b128 v[42:45], v20 offset:56320
	v_or_b32_e32 v69, 16, v46
	v_lshl_add_u32 v70, v69, 1, v47
	ds_read_b128 v[64:67], v70 offset:47104
	s_waitcnt lgkmcnt(4)
	v_mfma_f32_32x32x16_bf16 v[48:63], v[16:19], v[32:35], 0
	v_or_b32_e32 v69, v69, v37
	v_mul_u32_u24_e32 v69, 0x220, v69
	v_add3_u32 v69, 0, v69, v68
	ds_read_b64_tr_b16 v[130:131], v69 offset:12288
	ds_read_b64_tr_b16 v[132:133], v69 offset:14464
	ds_read_b64_tr_b16 v[136:137], v69 offset:14528
	ds_read_b64_tr_b16 v[134:135], v69 offset:12352
	ds_read_b128 v[138:141], v70 offset:56320
	v_or_b32_e32 v69, 32, v46
	v_lshl_add_u32 v70, v69, 1, v47
	v_or_b32_e32 v69, v69, v37
	s_waitcnt lgkmcnt(7)
	v_mfma_f32_32x32x16_bf16 v[16:31], v[16:19], v[38:41], 0
	v_mul_u32_u24_e32 v69, 0x220, v69
	v_add3_u32 v69, 0, v69, v68
	v_or_b32_e32 v46, 48, v46
	v_lshl_add_u32 v47, v46, 1, v47
	v_or_b32_e32 v37, v46, v37
	v_mul_u32_u24_e32 v37, 0x220, v37
	v_add3_u32 v37, 0, v37, v68
	s_waitcnt lgkmcnt(3)
	v_mfma_f32_32x32x16_bf16 v[48:63], v[64:67], v[130:133], v[48:63]
	s_lshl_b32 s6, s16, 3
	v_lshl_add_u32 v166, v36, 1, s6
	v_ashrrev_i32_e32 v167, 31, v166
	v_lshlrev_b64 v[168:169], 14, v[166:167]
	v_lshl_add_u64 v[168:169], s[8:9], 0, v[168:169]
	s_lshl_b32 s21, s33, 1
	s_and_b64 vcc, exec, s[4:5]
	s_waitcnt lgkmcnt(1)
	v_mfma_f32_32x32x16_bf16 v[16:31], v[64:67], v[134:137], v[16:31]
	ds_read_b128 v[64:67], v70 offset:47104
	ds_read_b64_tr_b16 v[142:143], v69 offset:12288
	ds_read_b64_tr_b16 v[144:145], v69 offset:14464
	ds_read_b64_tr_b16 v[148:149], v69 offset:14528
	ds_read_b64_tr_b16 v[146:147], v69 offset:12352
	ds_read_b128 v[150:153], v70 offset:56320
	s_waitcnt lgkmcnt(3)
	v_mfma_f32_32x32x16_bf16 v[48:63], v[64:67], v[142:145], v[48:63]
	s_waitcnt lgkmcnt(1)
	v_mfma_f32_32x32x16_bf16 v[16:31], v[64:67], v[146:149], v[16:31]
	ds_read_b128 v[64:67], v47 offset:47104
	ds_read_b64_tr_b16 v[154:155], v37 offset:12288
	ds_read_b64_tr_b16 v[156:157], v37 offset:14464
	ds_read_b64_tr_b16 v[160:161], v37 offset:14528
	ds_read_b64_tr_b16 v[158:159], v37 offset:12352
	ds_read_b128 v[162:165], v47 offset:56320
	s_waitcnt lgkmcnt(3)
	v_mfma_f32_32x32x16_bf16 v[48:63], v[64:67], v[154:157], v[48:63]
	s_waitcnt lgkmcnt(1)
	v_mfma_f32_32x32x16_bf16 v[16:31], v[64:67], v[158:161], v[16:31]
	s_nop 9
	v_cvt_pk_bf16_f32 v48, v48, v49
	v_cvt_pk_bf16_f32 v49, v50, v51
	v_cvt_pk_bf16_f32 v50, v52, v53
	v_lshlrev_b32_e32 v52, 13, v126
	v_lshl_or_b32 v52, v127, 12, v52
	v_lshl_or_b32 v108, v128, 4, v52
	v_lshl_add_u64 v[52:53], v[168:169], 0, v[108:109]
	v_mfma_f32_32x32x16_bf16 v[64:79], v[42:45], v[32:35], 0
	v_cvt_pk_bf16_f32 v16, v16, v17
	v_cvt_pk_bf16_f32 v17, v18, v19
	v_cvt_pk_bf16_f32 v18, v20, v21
	v_cvt_pk_bf16_f32 v19, v22, v23
	global_store_dwordx4 v[52:53], v[16:19], off offset:2048
	v_cvt_pk_bf16_f32 v51, v54, v55
	global_store_dwordx4 v[52:53], v[48:51], off
	v_mfma_f32_32x32x16_bf16 v[32:47], v[42:45], v[38:41], 0
	v_cvt_pk_bf16_f32 v16, v24, v25
	v_cvt_pk_bf16_f32 v17, v26, v27
	v_cvt_pk_bf16_f32 v18, v28, v29
	v_cvt_pk_bf16_f32 v19, v30, v31
	global_store_dwordx4 v[52:53], v[16:19], off offset:3072
	v_cvt_pk_bf16_f32 v48, v56, v57
	v_cvt_pk_bf16_f32 v49, v58, v59
	v_mfma_f32_32x32x16_bf16 v[64:79], v[138:141], v[130:133], v[64:79]
	v_or_b32_e32 v16, 1, v166
	v_ashrrev_i32_e32 v17, 31, v16
	v_lshlrev_b64 v[16:17], 14, v[16:17]
	v_lshl_add_u64 v[20:21], s[8:9], 0, v[16:17]
	v_lshl_add_u64 v[20:21], v[20:21], 0, v[108:109]
	v_cvt_pk_bf16_f32 v50, v60, v61
	v_cvt_pk_bf16_f32 v51, v62, v63
	v_mfma_f32_32x32x16_bf16 v[32:47], v[138:141], v[134:137], v[32:47]
	global_store_dwordx4 v[52:53], v[48:51], off offset:1024
	v_mfma_f32_32x32x16_bf16 v[64:79], v[150:153], v[142:145], v[64:79]
	v_mfma_f32_32x32x16_bf16 v[32:47], v[150:153], v[146:149], v[32:47]
	s_waitcnt lgkmcnt(0)
	v_mfma_f32_32x32x16_bf16 v[64:79], v[162:165], v[154:157], v[64:79]
	v_mfma_f32_32x32x16_bf16 v[32:47], v[162:165], v[158:161], v[32:47]
	s_nop 10
	v_cvt_pk_bf16_f32 v16, v64, v65
	v_cvt_pk_bf16_f32 v17, v66, v67
	v_cvt_pk_bf16_f32 v18, v68, v69
	v_cvt_pk_bf16_f32 v19, v70, v71
	global_store_dwordx4 v[20:21], v[16:19], off
	s_nop 1
	v_cvt_pk_bf16_f32 v16, v72, v73
	v_cvt_pk_bf16_f32 v17, v74, v75
	v_cvt_pk_bf16_f32 v18, v76, v77
	v_cvt_pk_bf16_f32 v19, v78, v79
	global_store_dwordx4 v[20:21], v[16:19], off offset:1024
	s_nop 1
	v_cvt_pk_bf16_f32 v16, v32, v33
	v_cvt_pk_bf16_f32 v17, v34, v35
	v_cvt_pk_bf16_f32 v18, v36, v37
	v_cvt_pk_bf16_f32 v19, v38, v39
	global_store_dwordx4 v[20:21], v[16:19], off offset:2048
	s_nop 1
	v_cvt_pk_bf16_f32 v16, v40, v41
	v_cvt_pk_bf16_f32 v17, v42, v43
	v_cvt_pk_bf16_f32 v18, v44, v45
	v_cvt_pk_bf16_f32 v19, v46, v47
	global_store_dwordx4 v[20:21], v[16:19], off offset:3072
	s_barrier
	s_cbranch_vccnz .LBB0_591

.LBB0_587:
	s_or_b64 exec, exec, s[4:5]
	s_add_i32 s93, s93, 1
	s_movk_i32 s94, 0x300
	s_bitcmp1_b32 s93, 0
	s_cselect_b32 s94, s94, 0xfffffcc0
	s_add_i32 s33, s33, s94
	s_cmp_gt_u32 s93, 5
	s_cselect_b64 s[4:5], -1, 0
	s_cmp_lt_u32 s93, 6
	s_cselect_b32 s17, s33, -1
	s_mov_b64 s[6:7], -1
	s_cmp_gt_i32 s17, -1
	v_lshlrev_b32_e32 v16, 2, v54
	s_waitcnt lgkmcnt(0)
	s_barrier
	s_cbranch_scc1 .LBB0_589
	v_lshlrev_b32_e32 v17, 2, v54
	s_mov_b64 s[6:7], 0
